# v17 + grid-barrier spin loops poll without s_sleep
# speedup vs baseline: 1.0008x; 1.0000x over previous
.LBB0_162:
	s_nop 0
	global_load_dword v2, v0, s[2:3] offset:32 sc1
	s_waitcnt vmcnt(0)
	v_and_b32_e32 v2, 0xffff0000, v2
	v_cmp_ne_u32_e32 vcc, v2, v1
	s_or_b64 s[4:5], vcc, s[4:5]
	s_andn2_b64 exec, exec, s[4:5]
	s_cbranch_execnz .LBB0_162

.LBB0_169:
	global_load_dword v15, v16, s[4:5] sc1
	s_waitcnt lgkmcnt(0)
	global_load_dword v0, v16, s[6:7] sc1
	global_load_dword v1, v16, s[8:9] sc1
	global_load_dword v2, v16, s[14:15] sc1
	global_load_dword v3, v16, s[16:17] sc1
	global_load_dword v4, v16, s[20:21] sc1
	global_load_dword v5, v16, s[22:23] sc1
	global_load_dword v6, v16, s[24:25] sc1
	global_load_dword v7, v16, s[26:27] sc1
	global_load_dword v8, v16, s[28:29] sc1
	global_load_dword v9, v16, s[30:31] sc1
	global_load_dword v10, v16, s[34:35] sc1
	global_load_dword v11, v16, s[36:37] sc1
	global_load_dword v12, v16, s[38:39] sc1
	global_load_dword v13, v16, s[40:41] sc1
	global_load_dword v14, v16, s[48:49] sc1
	s_mov_b64 s[50:51], -1
	s_mov_b64 s[56:57], -1
	s_waitcnt vmcnt(14)
	v_add_u32_e32 v17, v0, v15
	s_waitcnt vmcnt(13)
	v_add_u32_e32 v17, v17, v1
	s_waitcnt vmcnt(12)
	v_add_u32_e32 v17, v17, v2
	s_waitcnt vmcnt(11)
	v_add_u32_e32 v17, v17, v3
	s_waitcnt vmcnt(10)
	v_add_u32_e32 v17, v17, v4
	s_waitcnt vmcnt(9)
	v_add_u32_e32 v17, v17, v5
	s_waitcnt vmcnt(8)
	v_add_u32_e32 v17, v17, v6
	s_waitcnt vmcnt(7)
	v_add_u32_e32 v17, v17, v7
	s_waitcnt vmcnt(6)
	v_add_u32_e32 v17, v17, v8
	s_waitcnt vmcnt(5)
	v_add_u32_e32 v17, v17, v9
	s_waitcnt vmcnt(4)
	v_add_u32_e32 v17, v17, v10
	s_waitcnt vmcnt(3)
	v_add_u32_e32 v17, v17, v11
	s_waitcnt vmcnt(2)
	v_add_u32_e32 v17, v17, v12
	s_waitcnt vmcnt(1)
	v_add_u32_e32 v17, v17, v13
	s_waitcnt vmcnt(0)
	v_add_u32_e32 v17, v17, v14
	v_cmp_eq_u32_e32 vcc, s33, v17
	s_cbranch_vccnz .LBB0_168
	s_and_b32 s50, s53, 0xff
	s_cmp_eq_u32 s50, 0
	s_mov_b64 s[50:51], -1
	s_mov_b64 s[58:59], -1
	s_nop 0
	s_cbranch_scc0 .LBB0_173
	global_load_dword v17, v16, s[2:3] sc1
	s_waitcnt vmcnt(0)
	v_cmp_eq_u32_e32 vcc, 0, v17
	s_cbranch_vccnz .LBB0_175
	s_mov_b64 s[58:59], 0

.LBB0_187:
	s_and_b32 s24, s28, 0xff
	s_mov_b64 s[22:23], -1
	s_cmp_lg_u32 s24, 0
	s_mov_b64 s[26:27], -1
	s_nop 0
	s_cbranch_scc1 .LBB0_190
	global_load_dword v2, v0, s[8:9] sc1
	s_waitcnt vmcnt(0)
	v_cmp_eq_u32_e32 vcc, 0, v2
	s_cbranch_vccnz .LBB0_192
	s_mov_b64 s[26:27], 0
	s_mov_b64 s[24:25], -1

.LBB0_204:
	s_and_b32 s22, s28, 0xff
	s_cmp_lg_u32 s22, 0
	s_mov_b64 s[24:25], -1
	s_nop 0
	s_cbranch_scc1 .LBB0_207
	global_load_dword v1, v0, s[8:9] sc1
	s_waitcnt vmcnt(0)
	v_cmp_eq_u32_e32 vcc, 0, v1
	s_cbranch_vccnz .LBB0_209
	s_mov_b64 s[24:25], 0
	s_mov_b64 s[22:23], -1

.LBB0_237:
	global_load_dword v15, v16, s[4:5] sc1
	s_waitcnt lgkmcnt(0)
	global_load_dword v0, v16, s[6:7] sc1
	global_load_dword v1, v16, s[8:9] sc1
	global_load_dword v2, v16, s[14:15] sc1
	global_load_dword v3, v16, s[16:17] sc1
	global_load_dword v4, v16, s[20:21] sc1
	global_load_dword v5, v16, s[22:23] sc1
	global_load_dword v6, v16, s[24:25] sc1
	global_load_dword v7, v16, s[26:27] sc1
	global_load_dword v8, v16, s[28:29] sc1
	global_load_dword v9, v16, s[30:31] sc1
	global_load_dword v10, v16, s[34:35] sc1
	global_load_dword v11, v16, s[36:37] sc1
	global_load_dword v12, v16, s[38:39] sc1
	global_load_dword v13, v16, s[40:41] sc1
	global_load_dword v14, v16, s[56:57] sc1
	s_mov_b64 s[58:59], -1
	s_mov_b64 s[60:61], -1
	s_waitcnt vmcnt(14)
	v_add_u32_e32 v17, v0, v15
	s_waitcnt vmcnt(13)
	v_add_u32_e32 v17, v17, v1
	s_waitcnt vmcnt(12)
	v_add_u32_e32 v17, v17, v2
	s_waitcnt vmcnt(11)
	v_add_u32_e32 v17, v17, v3
	s_waitcnt vmcnt(10)
	v_add_u32_e32 v17, v17, v4
	s_waitcnt vmcnt(9)
	v_add_u32_e32 v17, v17, v5
	s_waitcnt vmcnt(8)
	v_add_u32_e32 v17, v17, v6
	s_waitcnt vmcnt(7)
	v_add_u32_e32 v17, v17, v7
	s_waitcnt vmcnt(6)
	v_add_u32_e32 v17, v17, v8
	s_waitcnt vmcnt(5)
	v_add_u32_e32 v17, v17, v9
	s_waitcnt vmcnt(4)
	v_add_u32_e32 v17, v17, v10
	s_waitcnt vmcnt(3)
	v_add_u32_e32 v17, v17, v11
	s_waitcnt vmcnt(2)
	v_add_u32_e32 v17, v17, v12
	s_waitcnt vmcnt(1)
	v_add_u32_e32 v17, v17, v13
	s_waitcnt vmcnt(0)
	v_add_u32_e32 v17, v17, v14
	v_cmp_eq_u32_e32 vcc, s33, v17
	s_cbranch_vccnz .LBB0_236
	s_and_b32 s55, s53, 0xff
	s_cmp_eq_u32 s55, 0
	s_mov_b64 s[62:63], -1
	s_nop 0
	s_cbranch_scc0 .LBB0_241
	global_load_dword v17, v16, s[2:3] sc1
	s_waitcnt vmcnt(0)
	v_cmp_eq_u32_e32 vcc, 0, v17
	s_cbranch_vccnz .LBB0_243
	s_mov_b64 s[62:63], 0

.LBB0_321:
	global_load_dword v15, v16, s[4:5] sc1
	s_waitcnt lgkmcnt(0)
	global_load_dword v0, v16, s[8:9] sc1
	global_load_dword v1, v16, s[14:15] sc1
	global_load_dword v2, v16, s[16:17] sc1
	global_load_dword v3, v16, s[20:21] sc1
	global_load_dword v4, v16, s[22:23] sc1
	global_load_dword v5, v16, s[24:25] sc1
	global_load_dword v6, v16, s[26:27] sc1
	global_load_dword v7, v16, s[28:29] sc1
	global_load_dword v8, v16, s[30:31] sc1
	global_load_dword v9, v16, s[34:35] sc1
	global_load_dword v10, v16, s[36:37] sc1
	global_load_dword v11, v16, s[38:39] sc1
	global_load_dword v12, v16, s[40:41] sc1
	global_load_dword v13, v16, s[60:61] sc1
	global_load_dword v14, v16, s[62:63] sc1
	s_mov_b64 s[64:65], -1
	s_mov_b64 s[66:67], -1
	s_waitcnt vmcnt(14)
	v_add_u32_e32 v17, v0, v15
	s_waitcnt vmcnt(13)
	v_add_u32_e32 v17, v17, v1
	s_waitcnt vmcnt(12)
	v_add_u32_e32 v17, v17, v2
	s_waitcnt vmcnt(11)
	v_add_u32_e32 v17, v17, v3
	s_waitcnt vmcnt(10)
	v_add_u32_e32 v17, v17, v4
	s_waitcnt vmcnt(9)
	v_add_u32_e32 v17, v17, v5
	s_waitcnt vmcnt(8)
	v_add_u32_e32 v17, v17, v6
	s_waitcnt vmcnt(7)
	v_add_u32_e32 v17, v17, v7
	s_waitcnt vmcnt(6)
	v_add_u32_e32 v17, v17, v8
	s_waitcnt vmcnt(5)
	v_add_u32_e32 v17, v17, v9
	s_waitcnt vmcnt(4)
	v_add_u32_e32 v17, v17, v10
	s_waitcnt vmcnt(3)
	v_add_u32_e32 v17, v17, v11
	s_waitcnt vmcnt(2)
	v_add_u32_e32 v17, v17, v12
	s_waitcnt vmcnt(1)
	v_add_u32_e32 v17, v17, v13
	s_waitcnt vmcnt(0)
	v_add_u32_e32 v17, v17, v14
	v_cmp_eq_u32_e32 vcc, s33, v17
	s_cbranch_vccnz .LBB0_320
	s_and_b32 s55, s53, 0xff
	s_cmp_eq_u32 s55, 0
	s_mov_b64 s[68:69], -1
	s_nop 0
	s_cbranch_scc0 .LBB0_325
	global_load_dword v17, v16, s[2:3] sc1
	s_waitcnt vmcnt(0)
	v_cmp_eq_u32_e32 vcc, 0, v17
	s_cbranch_vccnz .LBB0_327
	s_mov_b64 s[68:69], 0

.LBB0_339:
	s_and_b32 s26, s30, 0xff
	s_mov_b64 s[24:25], -1
	s_cmp_lg_u32 s26, 0
	s_mov_b64 s[28:29], -1
	s_nop 0
	s_cbranch_scc1 .LBB0_342
	global_load_dword v2, v0, s[14:15] sc1
	s_waitcnt vmcnt(0)
	v_cmp_eq_u32_e32 vcc, 0, v2
	s_cbranch_vccnz .LBB0_344
	s_mov_b64 s[28:29], 0
	s_mov_b64 s[26:27], -1

.LBB0_356:
	s_and_b32 s24, s30, 0xff
	s_cmp_lg_u32 s24, 0
	s_mov_b64 s[26:27], -1
	s_nop 0
	s_cbranch_scc1 .LBB0_359
	global_load_dword v1, v0, s[14:15] sc1
	s_waitcnt vmcnt(0)
	v_cmp_eq_u32_e32 vcc, 0, v1
	s_cbranch_vccnz .LBB0_361
	s_mov_b64 s[26:27], 0
	s_mov_b64 s[24:25], -1

.LBB0_671:
	global_load_dword v15, v16, s[4:5] sc1
	s_waitcnt lgkmcnt(0)
	global_load_dword v0, v16, s[6:7] sc1
	global_load_dword v1, v16, s[8:9] sc1
	global_load_dword v2, v16, s[12:13] sc1
	global_load_dword v3, v16, s[14:15] sc1
	global_load_dword v4, v16, s[16:17] sc1
	global_load_dword v5, v16, s[20:21] sc1
	global_load_dword v6, v16, s[22:23] sc1
	global_load_dword v7, v16, s[24:25] sc1
	global_load_dword v8, v16, s[26:27] sc1
	global_load_dword v9, v16, s[28:29] sc1
	global_load_dword v10, v16, s[30:31] sc1
	global_load_dword v11, v16, s[34:35] sc1
	global_load_dword v12, v16, s[36:37] sc1
	global_load_dword v13, v16, s[38:39] sc1
	global_load_dword v14, v16, s[40:41] sc1
	s_mov_b64 s[60:61], -1
	s_mov_b64 s[62:63], -1
	s_waitcnt vmcnt(14)
	v_add_u32_e32 v17, v0, v15
	s_waitcnt vmcnt(13)
	v_add_u32_e32 v17, v17, v1
	s_waitcnt vmcnt(12)
	v_add_u32_e32 v17, v17, v2
	s_waitcnt vmcnt(11)
	v_add_u32_e32 v17, v17, v3
	s_waitcnt vmcnt(10)
	v_add_u32_e32 v17, v17, v4
	s_waitcnt vmcnt(9)
	v_add_u32_e32 v17, v17, v5
	s_waitcnt vmcnt(8)
	v_add_u32_e32 v17, v17, v6
	s_waitcnt vmcnt(7)
	v_add_u32_e32 v17, v17, v7
	s_waitcnt vmcnt(6)
	v_add_u32_e32 v17, v17, v8
	s_waitcnt vmcnt(5)
	v_add_u32_e32 v17, v17, v9
	s_waitcnt vmcnt(4)
	v_add_u32_e32 v17, v17, v10
	s_waitcnt vmcnt(3)
	v_add_u32_e32 v17, v17, v11
	s_waitcnt vmcnt(2)
	v_add_u32_e32 v17, v17, v12
	s_waitcnt vmcnt(1)
	v_add_u32_e32 v17, v17, v13
	s_waitcnt vmcnt(0)
	v_add_u32_e32 v17, v17, v14
	v_cmp_eq_u32_e32 vcc, s33, v17
	s_cbranch_vccnz .LBB0_670
	s_and_b32 s55, s53, 0xff
	s_cmp_eq_u32 s55, 0
	s_mov_b64 s[64:65], -1
	s_nop 0
	s_cbranch_scc0 .LBB0_675
	global_load_dword v17, v16, s[2:3] sc1
	s_waitcnt vmcnt(0)
	v_cmp_eq_u32_e32 vcc, 0, v17
	s_cbranch_vccnz .LBB0_677
	s_mov_b64 s[64:65], 0

.LBB0_689:
	s_and_b32 s22, s26, 0xff
	s_mov_b64 s[20:21], -1
	s_cmp_lg_u32 s22, 0
	s_mov_b64 s[24:25], -1
	s_nop 0
	s_cbranch_scc1 .LBB0_692
	global_load_dword v2, v0, s[8:9] sc1
	s_waitcnt vmcnt(0)
	v_cmp_eq_u32_e32 vcc, 0, v2
	s_cbranch_vccnz .LBB0_694
	s_mov_b64 s[24:25], 0
	s_mov_b64 s[22:23], -1

.LBB0_706:
	s_and_b32 s20, s26, 0xff
	s_cmp_lg_u32 s20, 0
	s_mov_b64 s[22:23], -1
	s_nop 0
	s_cbranch_scc1 .LBB0_709
	global_load_dword v1, v0, s[8:9] sc1
	s_waitcnt vmcnt(0)
	v_cmp_eq_u32_e32 vcc, 0, v1
	s_cbranch_vccnz .LBB0_711
	s_mov_b64 s[22:23], 0
	s_mov_b64 s[20:21], -1

.LBB0_979:
	global_load_dword v15, v16, s[6:7] sc1
	s_waitcnt lgkmcnt(0)
	global_load_dword v0, v16, s[8:9] sc1
	global_load_dword v1, v16, s[12:13] sc1
	global_load_dword v2, v16, s[14:15] sc1
	global_load_dword v3, v16, s[16:17] sc1
	global_load_dword v4, v16, s[20:21] sc1
	global_load_dword v5, v16, s[22:23] sc1
	global_load_dword v6, v16, s[24:25] sc1
	global_load_dword v7, v16, s[26:27] sc1
	global_load_dword v8, v16, s[28:29] sc1
	global_load_dword v9, v16, s[30:31] sc1
	global_load_dword v10, v16, s[34:35] sc1
	global_load_dword v11, v16, s[36:37] sc1
	global_load_dword v12, v16, s[38:39] sc1
	global_load_dword v13, v16, s[40:41] sc1
	global_load_dword v14, v16, s[62:63] sc1
	s_mov_b64 s[64:65], -1
	s_mov_b64 s[66:67], -1
	s_waitcnt vmcnt(14)
	v_add_u32_e32 v17, v0, v15
	s_waitcnt vmcnt(13)
	v_add_u32_e32 v17, v17, v1
	s_waitcnt vmcnt(12)
	v_add_u32_e32 v17, v17, v2
	s_waitcnt vmcnt(11)
	v_add_u32_e32 v17, v17, v3
	s_waitcnt vmcnt(10)
	v_add_u32_e32 v17, v17, v4
	s_waitcnt vmcnt(9)
	v_add_u32_e32 v17, v17, v5
	s_waitcnt vmcnt(8)
	v_add_u32_e32 v17, v17, v6
	s_waitcnt vmcnt(7)
	v_add_u32_e32 v17, v17, v7
	s_waitcnt vmcnt(6)
	v_add_u32_e32 v17, v17, v8
	s_waitcnt vmcnt(5)
	v_add_u32_e32 v17, v17, v9
	s_waitcnt vmcnt(4)
	v_add_u32_e32 v17, v17, v10
	s_waitcnt vmcnt(3)
	v_add_u32_e32 v17, v17, v11
	s_waitcnt vmcnt(2)
	v_add_u32_e32 v17, v17, v12
	s_waitcnt vmcnt(1)
	v_add_u32_e32 v17, v17, v13
	s_waitcnt vmcnt(0)
	v_add_u32_e32 v17, v17, v14
	v_cmp_eq_u32_e32 vcc, s2, v17
	s_cbranch_vccnz .LBB0_978
	s_and_b32 s33, s3, 0xff
	s_cmp_eq_u32 s33, 0
	s_mov_b64 s[68:69], -1
	s_nop 0
	s_cbranch_scc0 .LBB0_983
	global_load_dword v17, v16, s[4:5] sc1
	s_waitcnt vmcnt(0)
	v_cmp_eq_u32_e32 vcc, 0, v17
	s_cbranch_vccnz .LBB0_985
	s_mov_b64 s[68:69], 0

.LBB0_997:
	s_and_b32 s3, s2, 0xff
	s_mov_b64 s[22:23], -1
	s_cmp_lg_u32 s3, 0
	s_mov_b64 s[26:27], -1
	s_nop 0
	s_cbranch_scc1 .LBB0_1000
	global_load_dword v2, v0, s[12:13] sc1
	s_waitcnt vmcnt(0)
	v_cmp_eq_u32_e32 vcc, 0, v2
	s_cbranch_vccnz .LBB0_1002
	s_mov_b64 s[26:27], 0
	s_mov_b64 s[24:25], -1

.LBB0_1014:
	s_and_b32 s3, s2, 0xff
	s_cmp_lg_u32 s3, 0
	s_mov_b64 s[24:25], -1
	s_nop 0
	s_cbranch_scc1 .LBB0_1017
	global_load_dword v1, v0, s[12:13] sc1
	s_waitcnt vmcnt(0)
	v_cmp_eq_u32_e32 vcc, 0, v1
	s_cbranch_vccnz .LBB0_1019
	s_mov_b64 s[24:25], 0
	s_mov_b64 s[22:23], -1

.LBB0_1055:
	global_load_dword v15, v16, s[6:7] sc1
	s_waitcnt lgkmcnt(0)
	global_load_dword v0, v16, s[8:9] sc1
	global_load_dword v1, v16, s[16:17] sc1
	global_load_dword v2, v16, s[20:21] sc1
	global_load_dword v3, v16, s[22:23] sc1
	global_load_dword v4, v16, s[24:25] sc1
	global_load_dword v5, v16, s[26:27] sc1
	global_load_dword v6, v16, s[28:29] sc1
	global_load_dword v7, v16, s[30:31] sc1
	global_load_dword v8, v16, s[34:35] sc1
	global_load_dword v9, v16, s[36:37] sc1
	global_load_dword v10, v16, s[38:39] sc1
	global_load_dword v11, v16, s[40:41] sc1
	global_load_dword v12, v16, s[62:63] sc1
	global_load_dword v13, v16, s[64:65] sc1
	global_load_dword v14, v16, s[66:67] sc1
	s_mov_b64 s[68:69], -1
	s_mov_b64 s[70:71], -1
	s_waitcnt vmcnt(14)
	v_add_u32_e32 v17, v0, v15
	s_waitcnt vmcnt(13)
	v_add_u32_e32 v17, v17, v1
	s_waitcnt vmcnt(12)
	v_add_u32_e32 v17, v17, v2
	s_waitcnt vmcnt(11)
	v_add_u32_e32 v17, v17, v3
	s_waitcnt vmcnt(10)
	v_add_u32_e32 v17, v17, v4
	s_waitcnt vmcnt(9)
	v_add_u32_e32 v17, v17, v5
	s_waitcnt vmcnt(8)
	v_add_u32_e32 v17, v17, v6
	s_waitcnt vmcnt(7)
	v_add_u32_e32 v17, v17, v7
	s_waitcnt vmcnt(6)
	v_add_u32_e32 v17, v17, v8
	s_waitcnt vmcnt(5)
	v_add_u32_e32 v17, v17, v9
	s_waitcnt vmcnt(4)
	v_add_u32_e32 v17, v17, v10
	s_waitcnt vmcnt(3)
	v_add_u32_e32 v17, v17, v11
	s_waitcnt vmcnt(2)
	v_add_u32_e32 v17, v17, v12
	s_waitcnt vmcnt(1)
	v_add_u32_e32 v17, v17, v13
	s_waitcnt vmcnt(0)
	v_add_u32_e32 v17, v17, v14
	v_cmp_eq_u32_e32 vcc, s2, v17
	s_cbranch_vccnz .LBB0_1054
	s_and_b32 s33, s3, 0xff
	s_cmp_eq_u32 s33, 0
	s_mov_b64 s[72:73], -1
	s_nop 0
	s_cbranch_scc0 .LBB0_1059
	global_load_dword v17, v16, s[4:5] sc1
	s_waitcnt vmcnt(0)
	v_cmp_eq_u32_e32 vcc, 0, v17
	s_cbranch_vccnz .LBB0_1061
	s_mov_b64 s[72:73], 0

.LBB0_1073:
	s_and_b32 s3, s2, 0xff
	s_mov_b64 s[26:27], -1
	s_cmp_lg_u32 s3, 0
	s_mov_b64 s[30:31], -1
	s_nop 0
	s_cbranch_scc1 .LBB0_1076
	global_load_dword v2, v0, s[16:17] sc1
	s_waitcnt vmcnt(0)
	v_cmp_eq_u32_e32 vcc, 0, v2
	s_cbranch_vccnz .LBB0_1078
	s_mov_b64 s[30:31], 0
	s_mov_b64 s[28:29], -1

.LBB0_1090:
	s_and_b32 s3, s2, 0xff
	s_cmp_lg_u32 s3, 0
	s_mov_b64 s[28:29], -1
	s_nop 0
	s_cbranch_scc1 .LBB0_1093
	global_load_dword v1, v0, s[16:17] sc1
	s_waitcnt vmcnt(0)
	v_cmp_eq_u32_e32 vcc, 0, v1
	s_cbranch_vccnz .LBB0_1095
	s_mov_b64 s[28:29], 0
	s_mov_b64 s[26:27], -1

.LBB0_1131:
	global_load_dword v15, v16, s[6:7] sc1
	s_waitcnt lgkmcnt(0)
	global_load_dword v0, v16, s[8:9] sc1
	global_load_dword v1, v16, s[14:15] sc1
	global_load_dword v2, v16, s[16:17] sc1
	global_load_dword v3, v16, s[20:21] sc1
	global_load_dword v4, v16, s[22:23] sc1
	global_load_dword v5, v16, s[24:25] sc1
	global_load_dword v6, v16, s[26:27] sc1
	global_load_dword v7, v16, s[28:29] sc1
	global_load_dword v8, v16, s[30:31] sc1
	global_load_dword v9, v16, s[34:35] sc1
	global_load_dword v10, v16, s[36:37] sc1
	global_load_dword v11, v16, s[38:39] sc1
	global_load_dword v12, v16, s[40:41] sc1
	global_load_dword v13, v16, s[64:65] sc1
	global_load_dword v14, v16, s[66:67] sc1
	s_mov_b64 s[68:69], -1
	s_mov_b64 s[70:71], -1
	s_waitcnt vmcnt(14)
	v_add_u32_e32 v17, v0, v15
	s_waitcnt vmcnt(13)
	v_add_u32_e32 v17, v17, v1
	s_waitcnt vmcnt(12)
	v_add_u32_e32 v17, v17, v2
	s_waitcnt vmcnt(11)
	v_add_u32_e32 v17, v17, v3
	s_waitcnt vmcnt(10)
	v_add_u32_e32 v17, v17, v4
	s_waitcnt vmcnt(9)
	v_add_u32_e32 v17, v17, v5
	s_waitcnt vmcnt(8)
	v_add_u32_e32 v17, v17, v6
	s_waitcnt vmcnt(7)
	v_add_u32_e32 v17, v17, v7
	s_waitcnt vmcnt(6)
	v_add_u32_e32 v17, v17, v8
	s_waitcnt vmcnt(5)
	v_add_u32_e32 v17, v17, v9
	s_waitcnt vmcnt(4)
	v_add_u32_e32 v17, v17, v10
	s_waitcnt vmcnt(3)
	v_add_u32_e32 v17, v17, v11
	s_waitcnt vmcnt(2)
	v_add_u32_e32 v17, v17, v12
	s_waitcnt vmcnt(1)
	v_add_u32_e32 v17, v17, v13
	s_waitcnt vmcnt(0)
	v_add_u32_e32 v17, v17, v14
	v_cmp_eq_u32_e32 vcc, s2, v17
	s_cbranch_vccnz .LBB0_1130
	s_and_b32 s33, s3, 0xff
	s_cmp_eq_u32 s33, 0
	s_mov_b64 s[72:73], -1
	s_nop 0
	s_cbranch_scc0 .LBB0_1135
	global_load_dword v17, v16, s[4:5] sc1
	s_waitcnt vmcnt(0)
	v_cmp_eq_u32_e32 vcc, 0, v17
	s_cbranch_vccnz .LBB0_1137
	s_mov_b64 s[72:73], 0

.LBB0_1149:
	s_and_b32 s3, s2, 0xff
	s_mov_b64 s[24:25], -1
	s_cmp_lg_u32 s3, 0
	s_mov_b64 s[28:29], -1
	s_nop 0
	s_cbranch_scc1 .LBB0_1152
	global_load_dword v2, v0, s[14:15] sc1
	s_waitcnt vmcnt(0)
	v_cmp_eq_u32_e32 vcc, 0, v2
	s_cbranch_vccnz .LBB0_1154
	s_mov_b64 s[28:29], 0
	s_mov_b64 s[26:27], -1

.LBB0_1166:
	s_and_b32 s3, s2, 0xff
	s_cmp_lg_u32 s3, 0
	s_mov_b64 s[26:27], -1
	s_nop 0
	s_cbranch_scc1 .LBB0_1169
	global_load_dword v1, v0, s[14:15] sc1
	s_waitcnt vmcnt(0)
	v_cmp_eq_u32_e32 vcc, 0, v1
	s_cbranch_vccnz .LBB0_1171
	s_mov_b64 s[26:27], 0
	s_mov_b64 s[24:25], -1

.LBB0_1241:
	global_load_dword v15, v16, s[8:9] sc1
	s_waitcnt lgkmcnt(0)
	global_load_dword v0, v16, s[12:13] sc1
	global_load_dword v1, v16, s[14:15] sc1
	global_load_dword v2, v16, s[16:17] sc1
	global_load_dword v3, v16, s[20:21] sc1
	global_load_dword v4, v16, s[24:25] sc1
	global_load_dword v5, v16, s[26:27] sc1
	global_load_dword v6, v16, s[28:29] sc1
	global_load_dword v7, v16, s[30:31] sc1
	global_load_dword v8, v16, s[34:35] sc1
	global_load_dword v9, v16, s[36:37] sc1
	global_load_dword v10, v16, s[38:39] sc1
	global_load_dword v11, v16, s[40:41] sc1
	global_load_dword v12, v16, s[66:67] sc1
	global_load_dword v13, v16, s[68:69] sc1
	global_load_dword v14, v16, s[70:71] sc1
	s_mov_b64 s[72:73], -1
	s_mov_b64 s[74:75], -1
	s_waitcnt vmcnt(14)
	v_add_u32_e32 v17, v0, v15
	s_waitcnt vmcnt(13)
	v_add_u32_e32 v17, v17, v1
	s_waitcnt vmcnt(12)
	v_add_u32_e32 v17, v17, v2
	s_waitcnt vmcnt(11)
	v_add_u32_e32 v17, v17, v3
	s_waitcnt vmcnt(10)
	v_add_u32_e32 v17, v17, v4
	s_waitcnt vmcnt(9)
	v_add_u32_e32 v17, v17, v5
	s_waitcnt vmcnt(8)
	v_add_u32_e32 v17, v17, v6
	s_waitcnt vmcnt(7)
	v_add_u32_e32 v17, v17, v7
	s_waitcnt vmcnt(6)
	v_add_u32_e32 v17, v17, v8
	s_waitcnt vmcnt(5)
	v_add_u32_e32 v17, v17, v9
	s_waitcnt vmcnt(4)
	v_add_u32_e32 v17, v17, v10
	s_waitcnt vmcnt(3)
	v_add_u32_e32 v17, v17, v11
	s_waitcnt vmcnt(2)
	v_add_u32_e32 v17, v17, v12
	s_waitcnt vmcnt(1)
	v_add_u32_e32 v17, v17, v13
	s_waitcnt vmcnt(0)
	v_add_u32_e32 v17, v17, v14
	v_cmp_eq_u32_e32 vcc, s2, v17
	s_cbranch_vccnz .LBB0_1240
	s_and_b32 s33, s3, 0xff
	s_cmp_eq_u32 s33, 0
	s_mov_b64 s[76:77], -1
	s_nop 0
	s_cbranch_scc0 .LBB0_1245
	global_load_dword v17, v16, s[6:7] sc1
	s_waitcnt vmcnt(0)
	v_cmp_eq_u32_e32 vcc, 0, v17
	s_cbranch_vccnz .LBB0_1247
	s_mov_b64 s[76:77], 0

.LBB0_1259:
	s_and_b32 s3, s2, 0xff
	s_mov_b64 s[26:27], -1
	s_cmp_lg_u32 s3, 0
	s_mov_b64 s[30:31], -1
	s_nop 0
	s_cbranch_scc1 .LBB0_1262
	global_load_dword v2, v0, s[14:15] sc1
	s_waitcnt vmcnt(0)
	v_cmp_eq_u32_e32 vcc, 0, v2
	s_cbranch_vccnz .LBB0_1264
	s_mov_b64 s[30:31], 0
	s_mov_b64 s[28:29], -1

.LBB0_1276:
	s_and_b32 s3, s2, 0xff
	s_cmp_lg_u32 s3, 0
	s_mov_b64 s[28:29], -1
	s_nop 0
	s_cbranch_scc1 .LBB0_1279
	global_load_dword v1, v0, s[14:15] sc1
	s_waitcnt vmcnt(0)
	v_cmp_eq_u32_e32 vcc, 0, v1
	s_cbranch_vccnz .LBB0_1281
	s_mov_b64 s[28:29], 0
	s_mov_b64 s[26:27], -1

.LBB0_1309:
	global_load_dword v15, v16, s[8:9] sc1
	s_waitcnt lgkmcnt(0)
	global_load_dword v0, v16, s[12:13] sc1
	global_load_dword v1, v16, s[14:15] sc1
	global_load_dword v2, v16, s[16:17] sc1
	global_load_dword v3, v16, s[20:21] sc1
	global_load_dword v4, v16, s[22:23] sc1
	global_load_dword v5, v16, s[24:25] sc1
	global_load_dword v6, v16, s[26:27] sc1
	global_load_dword v7, v16, s[28:29] sc1
	global_load_dword v8, v16, s[30:31] sc1
	global_load_dword v9, v16, s[34:35] sc1
	global_load_dword v10, v16, s[36:37] sc1
	global_load_dword v11, v16, s[38:39] sc1
	global_load_dword v12, v16, s[40:41] sc1
	global_load_dword v13, v16, s[66:67] sc1
	global_load_dword v14, v16, s[68:69] sc1
	s_mov_b64 s[70:71], -1
	s_mov_b64 s[72:73], -1
	s_waitcnt vmcnt(14)
	v_add_u32_e32 v17, v0, v15
	s_waitcnt vmcnt(13)
	v_add_u32_e32 v17, v17, v1
	s_waitcnt vmcnt(12)
	v_add_u32_e32 v17, v17, v2
	s_waitcnt vmcnt(11)
	v_add_u32_e32 v17, v17, v3
	s_waitcnt vmcnt(10)
	v_add_u32_e32 v17, v17, v4
	s_waitcnt vmcnt(9)
	v_add_u32_e32 v17, v17, v5
	s_waitcnt vmcnt(8)
	v_add_u32_e32 v17, v17, v6
	s_waitcnt vmcnt(7)
	v_add_u32_e32 v17, v17, v7
	s_waitcnt vmcnt(6)
	v_add_u32_e32 v17, v17, v8
	s_waitcnt vmcnt(5)
	v_add_u32_e32 v17, v17, v9
	s_waitcnt vmcnt(4)
	v_add_u32_e32 v17, v17, v10
	s_waitcnt vmcnt(3)
	v_add_u32_e32 v17, v17, v11
	s_waitcnt vmcnt(2)
	v_add_u32_e32 v17, v17, v12
	s_waitcnt vmcnt(1)
	v_add_u32_e32 v17, v17, v13
	s_waitcnt vmcnt(0)
	v_add_u32_e32 v17, v17, v14
	v_cmp_eq_u32_e32 vcc, s2, v17
	s_cbranch_vccnz .LBB0_1308
	s_and_b32 s33, s3, 0xff
	s_cmp_eq_u32 s33, 0
	s_mov_b64 s[74:75], -1
	s_nop 0
	s_cbranch_scc0 .LBB0_1313
	global_load_dword v17, v16, s[6:7] sc1
	s_waitcnt vmcnt(0)
	v_cmp_eq_u32_e32 vcc, 0, v17
	s_cbranch_vccnz .LBB0_1315
	s_mov_b64 s[74:75], 0

.LBB0_1371:
	global_load_dword v15, v16, s[12:13] sc1
	s_waitcnt lgkmcnt(0)
	global_load_dword v0, v16, s[14:15] sc1
	global_load_dword v1, v16, s[16:17] sc1
	global_load_dword v2, v16, s[20:21] sc1
	global_load_dword v3, v16, s[22:23] sc1
	global_load_dword v4, v16, s[24:25] sc1
	global_load_dword v5, v16, s[26:27] sc1
	global_load_dword v6, v16, s[28:29] sc1
	global_load_dword v7, v16, s[30:31] sc1
	global_load_dword v8, v16, s[34:35] sc1
	global_load_dword v9, v16, s[36:37] sc1
	global_load_dword v10, v16, s[38:39] sc1
	global_load_dword v11, v16, s[40:41] sc1
	global_load_dword v12, v16, s[58:59] sc1
	global_load_dword v13, v16, s[66:67] sc1
	global_load_dword v14, v16, s[68:69] sc1
	s_mov_b64 s[70:71], -1
	s_mov_b64 s[72:73], -1
	s_waitcnt vmcnt(14)
	v_add_u32_e32 v17, v0, v15
	s_waitcnt vmcnt(13)
	v_add_u32_e32 v17, v17, v1
	s_waitcnt vmcnt(12)
	v_add_u32_e32 v17, v17, v2
	s_waitcnt vmcnt(11)
	v_add_u32_e32 v17, v17, v3
	s_waitcnt vmcnt(10)
	v_add_u32_e32 v17, v17, v4
	s_waitcnt vmcnt(9)
	v_add_u32_e32 v17, v17, v5
	s_waitcnt vmcnt(8)
	v_add_u32_e32 v17, v17, v6
	s_waitcnt vmcnt(7)
	v_add_u32_e32 v17, v17, v7
	s_waitcnt vmcnt(6)
	v_add_u32_e32 v17, v17, v8
	s_waitcnt vmcnt(5)
	v_add_u32_e32 v17, v17, v9
	s_waitcnt vmcnt(4)
	v_add_u32_e32 v17, v17, v10
	s_waitcnt vmcnt(3)
	v_add_u32_e32 v17, v17, v11
	s_waitcnt vmcnt(2)
	v_add_u32_e32 v17, v17, v12
	s_waitcnt vmcnt(1)
	v_add_u32_e32 v17, v17, v13
	s_waitcnt vmcnt(0)
	v_add_u32_e32 v17, v17, v14
	v_cmp_eq_u32_e32 vcc, s2, v17
	s_cbranch_vccnz .LBB0_1370
	s_and_b32 s6, s3, 0xff
	s_cmp_eq_u32 s6, 0
	s_mov_b64 s[74:75], -1
	s_nop 0
	s_cbranch_scc0 .LBB0_1375
	global_load_dword v17, v16, s[8:9] sc1
	s_waitcnt vmcnt(0)
	v_cmp_eq_u32_e32 vcc, 0, v17
	s_cbranch_vccnz .LBB0_1377
	s_mov_b64 s[74:75], 0

.LBB0_1791:
	global_load_dword v15, v16, s[6:7] sc1
	s_waitcnt lgkmcnt(0)
	global_load_dword v0, v16, s[8:9] sc1
	global_load_dword v1, v16, s[12:13] sc1
	global_load_dword v2, v16, s[14:15] sc1
	global_load_dword v3, v16, s[16:17] sc1
	global_load_dword v4, v16, s[20:21] sc1
	global_load_dword v5, v16, s[22:23] sc1
	global_load_dword v6, v16, s[24:25] sc1
	global_load_dword v7, v16, s[26:27] sc1
	global_load_dword v8, v16, s[28:29] sc1
	global_load_dword v9, v16, s[30:31] sc1
	global_load_dword v10, v16, s[34:35] sc1
	global_load_dword v11, v16, s[36:37] sc1
	global_load_dword v12, v16, s[38:39] sc1
	global_load_dword v13, v16, s[40:41] sc1
	global_load_dword v14, v16, s[52:53] sc1
	s_mov_b64 s[54:55], -1
	s_mov_b64 s[56:57], -1
	s_waitcnt vmcnt(14)
	v_add_u32_e32 v17, v0, v15
	s_waitcnt vmcnt(13)
	v_add_u32_e32 v17, v17, v1
	s_waitcnt vmcnt(12)
	v_add_u32_e32 v17, v17, v2
	s_waitcnt vmcnt(11)
	v_add_u32_e32 v17, v17, v3
	s_waitcnt vmcnt(10)
	v_add_u32_e32 v17, v17, v4
	s_waitcnt vmcnt(9)
	v_add_u32_e32 v17, v17, v5
	s_waitcnt vmcnt(8)
	v_add_u32_e32 v17, v17, v6
	s_waitcnt vmcnt(7)
	v_add_u32_e32 v17, v17, v7
	s_waitcnt vmcnt(6)
	v_add_u32_e32 v17, v17, v8
	s_waitcnt vmcnt(5)
	v_add_u32_e32 v17, v17, v9
	s_waitcnt vmcnt(4)
	v_add_u32_e32 v17, v17, v10
	s_waitcnt vmcnt(3)
	v_add_u32_e32 v17, v17, v11
	s_waitcnt vmcnt(2)
	v_add_u32_e32 v17, v17, v12
	s_waitcnt vmcnt(1)
	v_add_u32_e32 v17, v17, v13
	s_waitcnt vmcnt(0)
	v_add_u32_e32 v17, v17, v14
	v_cmp_eq_u32_e32 vcc, s33, v17
	s_cbranch_vccnz .LBB0_1790
	s_and_b32 s54, s60, 0xff
	s_cmp_eq_u32 s54, 0
	s_mov_b64 s[54:55], -1
	s_mov_b64 s[58:59], -1
	s_nop 0
	s_cbranch_scc0 .LBB0_1795
	global_load_dword v17, v16, s[2:3] sc1
	s_waitcnt vmcnt(0)
	v_cmp_eq_u32_e32 vcc, 0, v17
	s_cbranch_vccnz .LBB0_1797
	s_mov_b64 s[58:59], 0

.LBB0_1809:
	s_and_b32 s24, s28, 0xff
	s_mov_b64 s[22:23], -1
	s_cmp_lg_u32 s24, 0
	s_mov_b64 s[26:27], -1
	s_nop 0
	s_cbranch_scc1 .LBB0_1812
	global_load_dword v2, v0, s[12:13] sc1
	s_waitcnt vmcnt(0)
	v_cmp_eq_u32_e32 vcc, 0, v2
	s_cbranch_vccnz .LBB0_1814
	s_mov_b64 s[26:27], 0
	s_mov_b64 s[24:25], -1

.LBB0_1826:
	s_and_b32 s22, s28, 0xff
	s_cmp_lg_u32 s22, 0
	s_mov_b64 s[24:25], -1
	s_nop 0
	s_cbranch_scc1 .LBB0_1829
	global_load_dword v1, v0, s[12:13] sc1
	s_waitcnt vmcnt(0)
	v_cmp_eq_u32_e32 vcc, 0, v1
	s_cbranch_vccnz .LBB0_1831
	s_mov_b64 s[24:25], 0
	s_mov_b64 s[22:23], -1

.LBB0_1871:
	global_load_dword v15, v16, s[6:7] sc1
	s_waitcnt lgkmcnt(0)
	global_load_dword v0, v16, s[8:9] sc1
	global_load_dword v1, v16, s[12:13] sc1
	global_load_dword v2, v16, s[16:17] sc1
	global_load_dword v3, v16, s[20:21] sc1
	global_load_dword v4, v16, s[22:23] sc1
	global_load_dword v5, v16, s[24:25] sc1
	global_load_dword v6, v16, s[26:27] sc1
	global_load_dword v7, v16, s[28:29] sc1
	global_load_dword v8, v16, s[30:31] sc1
	global_load_dword v9, v16, s[34:35] sc1
	global_load_dword v10, v16, s[36:37] sc1
	global_load_dword v11, v16, s[38:39] sc1
	global_load_dword v12, v16, s[40:41] sc1
	global_load_dword v13, v16, s[52:53] sc1
	global_load_dword v14, v16, s[54:55] sc1
	s_mov_b64 s[56:57], -1
	s_mov_b64 s[58:59], -1
	s_waitcnt vmcnt(14)
	v_add_u32_e32 v17, v0, v15
	s_waitcnt vmcnt(13)
	v_add_u32_e32 v17, v17, v1
	s_waitcnt vmcnt(12)
	v_add_u32_e32 v17, v17, v2
	s_waitcnt vmcnt(11)
	v_add_u32_e32 v17, v17, v3
	s_waitcnt vmcnt(10)
	v_add_u32_e32 v17, v17, v4
	s_waitcnt vmcnt(9)
	v_add_u32_e32 v17, v17, v5
	s_waitcnt vmcnt(8)
	v_add_u32_e32 v17, v17, v6
	s_waitcnt vmcnt(7)
	v_add_u32_e32 v17, v17, v7
	s_waitcnt vmcnt(6)
	v_add_u32_e32 v17, v17, v8
	s_waitcnt vmcnt(5)
	v_add_u32_e32 v17, v17, v9
	s_waitcnt vmcnt(4)
	v_add_u32_e32 v17, v17, v10
	s_waitcnt vmcnt(3)
	v_add_u32_e32 v17, v17, v11
	s_waitcnt vmcnt(2)
	v_add_u32_e32 v17, v17, v12
	s_waitcnt vmcnt(1)
	v_add_u32_e32 v17, v17, v13
	s_waitcnt vmcnt(0)
	v_add_u32_e32 v17, v17, v14
	v_cmp_eq_u32_e32 vcc, s33, v17
	s_cbranch_vccnz .LBB0_1870
	s_and_b32 s56, s62, 0xff
	s_cmp_eq_u32 s56, 0
	s_mov_b64 s[56:57], -1
	s_mov_b64 s[60:61], -1
	s_nop 0
	s_cbranch_scc0 .LBB0_1875
	global_load_dword v17, v16, s[2:3] sc1
	s_waitcnt vmcnt(0)
	v_cmp_eq_u32_e32 vcc, 0, v17
	s_cbranch_vccnz .LBB0_1877
	s_mov_b64 s[60:61], 0

.LBB0_1889:
	s_and_b32 s26, s30, 0xff
	s_mov_b64 s[24:25], -1
	s_cmp_lg_u32 s26, 0
	s_mov_b64 s[28:29], -1
	s_nop 0
	s_cbranch_scc1 .LBB0_1892
	global_load_dword v2, v0, s[12:13] sc1
	s_waitcnt vmcnt(0)
	v_cmp_eq_u32_e32 vcc, 0, v2
	s_cbranch_vccnz .LBB0_1894
	s_mov_b64 s[28:29], 0
	s_mov_b64 s[26:27], -1

.LBB0_1906:
	s_and_b32 s24, s30, 0xff
	s_cmp_lg_u32 s24, 0
	s_mov_b64 s[26:27], -1
	s_nop 0
	s_cbranch_scc1 .LBB0_1909
	global_load_dword v1, v0, s[12:13] sc1
	s_waitcnt vmcnt(0)
	v_cmp_eq_u32_e32 vcc, 0, v1
	s_cbranch_vccnz .LBB0_1911
	s_mov_b64 s[26:27], 0
	s_mov_b64 s[24:25], -1

.LBB0_1947:
	global_load_dword v15, v16, s[6:7] sc1
	s_waitcnt lgkmcnt(0)
	global_load_dword v0, v16, s[8:9] sc1
	global_load_dword v1, v16, s[10:11] sc1
	global_load_dword v2, v16, s[12:13] sc1
	global_load_dword v3, v16, s[14:15] sc1
	global_load_dword v4, v16, s[16:17] sc1
	global_load_dword v5, v16, s[20:21] sc1
	global_load_dword v6, v16, s[22:23] sc1
	global_load_dword v7, v16, s[24:25] sc1
	global_load_dword v8, v16, s[26:27] sc1
	global_load_dword v9, v16, s[28:29] sc1
	global_load_dword v10, v16, s[30:31] sc1
	global_load_dword v11, v16, s[34:35] sc1
	global_load_dword v12, v16, s[36:37] sc1
	global_load_dword v13, v16, s[38:39] sc1
	global_load_dword v14, v16, s[40:41] sc1
	s_mov_b64 s[52:53], -1
	s_mov_b64 s[54:55], -1
	s_waitcnt vmcnt(14)
	v_add_u32_e32 v17, v0, v15
	s_waitcnt vmcnt(13)
	v_add_u32_e32 v17, v17, v1
	s_waitcnt vmcnt(12)
	v_add_u32_e32 v17, v17, v2
	s_waitcnt vmcnt(11)
	v_add_u32_e32 v17, v17, v3
	s_waitcnt vmcnt(10)
	v_add_u32_e32 v17, v17, v4
	s_waitcnt vmcnt(9)
	v_add_u32_e32 v17, v17, v5
	s_waitcnt vmcnt(8)
	v_add_u32_e32 v17, v17, v6
	s_waitcnt vmcnt(7)
	v_add_u32_e32 v17, v17, v7
	s_waitcnt vmcnt(6)
	v_add_u32_e32 v17, v17, v8
	s_waitcnt vmcnt(5)
	v_add_u32_e32 v17, v17, v9
	s_waitcnt vmcnt(4)
	v_add_u32_e32 v17, v17, v10
	s_waitcnt vmcnt(3)
	v_add_u32_e32 v17, v17, v11
	s_waitcnt vmcnt(2)
	v_add_u32_e32 v17, v17, v12
	s_waitcnt vmcnt(1)
	v_add_u32_e32 v17, v17, v13
	s_waitcnt vmcnt(0)
	v_add_u32_e32 v17, v17, v14
	v_cmp_eq_u32_e32 vcc, s33, v17
	s_cbranch_vccnz .LBB0_1946
	s_and_b32 s52, s47, 0xff
	s_cmp_eq_u32 s52, 0
	s_mov_b64 s[52:53], -1
	s_mov_b64 s[56:57], -1
	s_nop 0
	s_cbranch_scc0 .LBB0_1951
	global_load_dword v17, v16, s[2:3] sc1
	s_waitcnt vmcnt(0)
	v_cmp_eq_u32_e32 vcc, 0, v17
	s_cbranch_vccnz .LBB0_1953
	s_mov_b64 s[56:57], 0

.LBB0_1965:
	s_and_b32 s22, s19, 0xff
	s_mov_b64 s[20:21], -1
	s_cmp_lg_u32 s22, 0
	s_mov_b64 s[24:25], -1
	s_nop 0
	s_cbranch_scc1 .LBB0_1968
	global_load_dword v2, v0, s[10:11] sc1
	s_waitcnt vmcnt(0)
	v_cmp_eq_u32_e32 vcc, 0, v2
	s_cbranch_vccnz .LBB0_1970
	s_mov_b64 s[24:25], 0
	s_mov_b64 s[22:23], -1

.LBB0_1982:
	s_and_b32 s20, s19, 0xff
	s_cmp_lg_u32 s20, 0
	s_mov_b64 s[22:23], -1
	s_nop 0
	s_cbranch_scc1 .LBB0_1985
	global_load_dword v1, v0, s[10:11] sc1
	s_waitcnt vmcnt(0)
	v_cmp_eq_u32_e32 vcc, 0, v1
	s_cbranch_vccnz .LBB0_1987
	s_mov_b64 s[22:23], 0
	s_mov_b64 s[20:21], -1
